# 8 (was 6) layer-1 weight conversion tiles per idle workgroup moved into the sample mixer phase
# speedup vs baseline: 1.0183x; 1.0114x over previous
.LBB0_225:
	v_writelane_b32 v255, s12, 6
	s_andn2_b64 vcc, exec, s[4:5]
	s_nop 0
	v_writelane_b32 v255, s13, 7
	v_writelane_b32 v255, s0, 10
	s_nop 1
	v_writelane_b32 v255, s1, 11
	v_writelane_b32 v255, s77, 12
	s_cbranch_vccnz .LBB0_308
	s_cmp_eq_u32 s6, 14
	s_cselect_b32 vcc_lo, 1, 0
	v_writelane_b32 v255, vcc_lo, 30
	s_add_i32 s20, s6, 18
	s_cmp_gt_u32 s20, 38
	s_cselect_b64 s[0:1], -1, 0
	s_lshl_b32 s4, s74, 2
	v_writelane_b32 v255, s0, 4
	s_ashr_i32 s5, s4, 31
	s_lshl_b64 s[4:5], s[4:5], 2
	v_writelane_b32 v255, s1, 5
	v_readlane_b32 s0, v252, 24
	s_add_u32 s4, s0, s4
	v_readlane_b32 s0, v252, 25
	s_addc_u32 s5, s0, s5
	v_writelane_b32 v255, s4, 13
	s_cmp_lt_u32 s20, 39
	s_mov_b32 s0, 0x4c25000
	v_writelane_b32 v255, s5, 14
	s_movk_i32 s4, 0x760
	v_readlane_b32 s16, v255, 6
	v_readlane_b32 s17, v255, 7
	s_cselect_b32 s34, s4, 0x600
	s_and_b64 s[4:5], s[16:17], exec
	v_readlane_b32 s36, v252, 4
	s_cselect_b32 s4, s0, 0x9c25000
	v_readlane_b32 s50, v252, 18
	v_readlane_b32 s51, v252, 19
	s_add_u32 s0, s50, s4
	s_addc_u32 s1, s51, 0
	v_writelane_b32 v255, s0, 8
	s_and_b64 s[4:5], s[16:17], exec
	v_readlane_b32 s52, v253, 8
	v_writelane_b32 v255, s1, 9
	s_mov_b32 s0, 0xfd25000
	s_cselect_b32 s4, s0, 0x6425000
	s_add_u32 s0, s50, s4
	s_addc_u32 s1, s51, 0
	v_writelane_b32 v255, s0, 15
	v_readlane_b32 s66, v253, 22
	v_readlane_b32 s67, v253, 23
	v_writelane_b32 v255, s1, 16
	v_readlane_b32 s24, v252, 34
	v_readlane_b32 s0, v255, 2
	s_lshl_b32 s4, s0, 7
	s_ashr_i32 s5, s4, 31
	s_lshl_b64 s[4:5], s[4:5], 2
	v_readlane_b32 s1, v255, 3
	s_mov_b32 s26, s0
	s_add_u32 s0, s66, s4
	s_addc_u32 s1, s67, s5
	v_writelane_b32 v255, s0, 17
	s_and_b64 s[20:21], s[16:17], exec
	s_cselect_b32 s35, 4, 64
	v_writelane_b32 v255, s1, 18
	s_movk_i32 s0, 0x100
	s_cselect_b32 s13, s0, 0x1100
	s_cselect_b32 s14, 8, 12
	s_ashr_i32 s27, s26, 31
	s_lshl_b32 s0, s13, 8
	s_lshl_b32 s15, s13, 7
	s_lshr_b32 s77, s13, 6
	s_lshl_b32 s22, s13, 6
	s_lshl_b64 s[20:21], s[26:27], 2
	v_writelane_b32 v255, s0, 19
	v_readlane_b32 s25, v252, 35
	s_add_u32 s0, s24, s20
	v_cvt_f32_ubyte0_e32 v0, s35
	s_addc_u32 s1, s25, s21
	v_rcp_iflag_f32_e32 v0, v0
	s_add_u32 s20, s50, s20
	v_writelane_b32 v255, s0, 20
	s_addc_u32 s21, s51, s21
	v_readlane_b32 s38, v252, 6
	v_writelane_b32 v255, s1, 21
	s_add_u32 s0, s20, 0x4b24008
	s_addc_u32 s1, s21, 0
	v_mul_f32_e32 v0, 0x4f7ffffe, v0
	v_readlane_b32 s39, v252, 7
	s_add_u32 s28, s38, s4
	v_cvt_u32_f32_e32 v0, v0
	s_addc_u32 s29, s39, s5
	s_and_b64 s[4:5], s[16:17], exec
	s_cselect_b32 s16, 1, 16
	v_readfirstlane_b32 s5, v0
	v_cvt_f32_ubyte0_e32 v0, s16
	v_rcp_iflag_f32_e32 v0, v0
	v_writelane_b32 v255, s0, 22
	s_sub_i32 s4, 0, s35
	s_mul_i32 s4, s4, s5
	v_mul_f32_e32 v0, 0x4f7ffffe, v0
	v_cvt_u32_f32_e32 v0, v0
	v_writelane_b32 v255, s1, 23
	s_mov_b32 s0, s26
	v_writelane_b32 v255, s0, 2
	s_mul_hi_u32 s4, s5, s4
	s_mov_b32 s75, 0x60000
	v_writelane_b32 v255, s1, 3
	s_add_i32 s0, s5, s4
	s_sub_i32 s4, 0, s16
	v_readfirstlane_b32 s5, v0
	s_mul_i32 s4, s4, s5
	s_mul_hi_u32 s4, s5, s4
	s_mov_b32 s76, 0x8000
	s_mov_b32 s23, s95
	s_lshl_b32 s17, s26, 1
	v_writelane_b32 v255, s0, 24
	s_add_i32 s0, s5, s4
	s_sub_i32 s12, 0, s77
	s_mov_b32 s96, s71
	v_readlane_b32 s37, v252, 5
	v_readlane_b32 s40, v252, 8
	v_readlane_b32 s41, v252, 9
	v_readlane_b32 s42, v252, 10
	v_readlane_b32 s43, v252, 11
	v_readlane_b32 s44, v252, 12
	v_readlane_b32 s45, v252, 13
	v_readlane_b32 s46, v252, 14
	v_readlane_b32 s47, v252, 15
	v_readlane_b32 s48, v252, 16
	v_readlane_b32 s49, v252, 17
	v_readlane_b32 s53, v253, 9
	v_readlane_b32 s54, v253, 10
	v_readlane_b32 s55, v253, 11
	v_readlane_b32 s56, v253, 12
	v_readlane_b32 s57, v253, 13
	v_readlane_b32 s58, v253, 14
	v_readlane_b32 s59, v253, 15
	v_readlane_b32 s60, v253, 16
	v_readlane_b32 s61, v253, 17
	v_readlane_b32 s62, v253, 18
	v_readlane_b32 s63, v253, 19
	v_readlane_b32 s64, v253, 20
	v_readlane_b32 s65, v253, 21
	s_branch .LBB0_229

.Lattn_static:
	s_waitcnt lgkmcnt(0)
	ds_read_b32 v2, v196 offset:4
	v_readlane_b32 s99, v255, 12
	s_waitcnt lgkmcnt(0)
	v_readfirstlane_b32 s24, v2
	s_nop 3
	s_and_b32 s25, s99, 7
	s_lshl_b32 s25, s25, 6
	s_lshr_b32 s26, s99, 3
	s_or_b32 s25, s25, s26
	s_add_i32 s25, s25, 0x100
	s_cmpk_lt_u32 s99, 0x100
	s_cselect_b32 s26, 0, 1
	s_add_i32 s26, s26, s24
	s_add_i32 s24, s24, 1
	s_cmp_eq_u32 s26, 1
	s_cselect_b32 s98, s25, 0x300
	s_cmp_eq_u32 s26, 0
	s_cselect_b32 s98, s99, s98
	v_readlane_b32 vcc_hi, v255, 30
	s_nop 3
	s_cmpk_lt_u32 s99, 0x100
	s_cbranch_scc1 .Lcv_no
	s_cmp_eq_u32 vcc_hi, 0
	s_cbranch_scc1 .Lcv_no
	s_cmp_lt_u32 s26, 2
	s_cbranch_scc1 .Lcv_no
	s_cmp_gt_u32 s26, 9
	s_cbranch_scc1 .Lcv_no
	s_sub_u32 vcc_lo, s26, 2
	s_lshl_b32 vcc_lo, vcc_lo, 8
	s_add_u32 s98, s99, vcc_lo
	s_add_u32 s98, s98, 0x460
	s_branch .Lcv_keep
